# attention body unrolled by two: LDS stage offset folded into ds_read/DMA immediates (no per-iteration address VALU), SGPR-base DMA addressing, rescale-test permlane moved to rare path
# speedup vs baseline: 1.0170x; 1.0170x over previous
.Lfa_body:
	v_add_u32_e32 v0, s20, v156
	v_add_u32_e32 v2, v0, v148
	v_add_u32_e32 v3, v0, v150
	v_add_u32_e32 v4, v0, v152
	v_add_u32_e32 v5, v0, v154
	v_add_u32_e32 v0, s20, v157
	v_add_u32_e32 v0, 0x10000, v0
	v_add_u32_e32 v6, v0, v149
	v_add_u32_e32 v7, v0, v151
	v_add_u32_e32 v8, v0, v153
	v_add_u32_e32 v9, v0, v155
	v_subrev_u32_e32 v10, s86, v144
	v_subrev_u32_e32 v11, s76, v146
.Lfa_top_1:
	s_waitcnt vmcnt(0) lgkmcnt(0)
	s_barrier
	ds_read_b128 v[160:163], v2 offset:32768
	ds_read_b128 v[164:167], v2 offset:40960
	ds_read_b128 v[168:171], v3 offset:32768
	ds_read_b128 v[224:227], v3 offset:40960
	ds_read_b128 v[228:231], v4 offset:32768
	ds_read_b128 v[232:235], v4 offset:40960
	ds_read_b128 v[236:239], v5 offset:32768
	ds_read_b128 v[244:247], v5 offset:40960
	ds_read_b128 v[248:251], v2 offset:49152
	ds_read_b128 v[252:255], v2 offset:57344
	s_mov_b32 s80, 0
	s_waitcnt lgkmcnt(8)
	v_mfma_f32_32x32x16_bf16 v[96:111], v[160:163], v[128:131], v[80:95]
	ds_read_b128 v[160:163], v3 offset:49152
	s_sub_i32 s16, s8, 64
	s_mov_b32 s17, 0
	s_lshl_b64 s[16:17], s[16:17], 11
	s_add_u32 s16, s16, s86
	s_addc_u32 s17, s17, s87
	s_add_u32 s18, s76, s6
	s_addc_u32 s19, s77, s7
	s_add_u32 s18, s18, 0x6d08000
	s_addc_u32 s19, s19, 0
	s_add_i32 m0, s24, 0x0
	s_nop 0
	global_load_lds_dwordx4 v10, s[16:17]
	v_mfma_f32_32x32x16_bf16 v[112:127], v[164:167], v[128:131], v[80:95]
	ds_read_b128 v[164:167], v3 offset:57344
	s_add_i32 m0, s24, 0x2000
	s_add_u32 s16, s16, 0x10000
	s_addc_u32 s17, s17, 0
	global_load_lds_dwordx4 v10, s[16:17]
	s_waitcnt lgkmcnt(8)
	v_mfma_f32_32x32x16_bf16 v[96:111], v[168:171], v[132:135], v[96:111]
	ds_read_b128 v[168:171], v4 offset:49152
	s_add_i32 m0, s24, 0x10000
	s_nop 0
	global_load_lds_dwordx4 v11, s[18:19]
	v_mfma_f32_32x32x16_bf16 v[112:127], v[224:227], v[132:135], v[112:127]
	ds_read_b128 v[224:227], v4 offset:57344
	s_add_i32 m0, s24, 0x12000
	s_add_u32 s18, s18, 0x2000
	s_addc_u32 s19, s19, 0
	global_load_lds_dwordx4 v11, s[18:19]
	s_waitcnt lgkmcnt(8)
	v_mfma_f32_32x32x16_bf16 v[96:111], v[228:231], v[136:139], v[96:111]
	ds_read_b128 v[228:231], v5 offset:49152
	s_add_i32 m0, s24, 0x4000
	s_add_u32 s16, s16, 0x10000
	s_addc_u32 s17, s17, 0
	global_load_lds_dwordx4 v10, s[16:17]
	v_mfma_f32_32x32x16_bf16 v[112:127], v[232:235], v[136:139], v[112:127]
	ds_read_b128 v[232:235], v5 offset:57344
	s_add_i32 m0, s24, 0x6000
	s_add_u32 s16, s16, 0x10000
	s_addc_u32 s17, s17, 0
	global_load_lds_dwordx4 v10, s[16:17]
	s_waitcnt lgkmcnt(8)
	v_mfma_f32_32x32x16_bf16 v[96:111], v[236:239], v[140:143], v[96:111]
	ds_read_b128 v[236:239], v6 offset:32768
	s_add_i32 m0, s24, 0x14000
	s_add_u32 s18, s18, 0x2000
	s_addc_u32 s19, s19, 0
	global_load_lds_dwordx4 v11, s[18:19]
	v_mfma_f32_32x32x16_bf16 v[112:127], v[244:247], v[140:143], v[112:127]
	ds_read_b128 v[244:247], v6 offset:36864
	s_add_i32 m0, s24, 0x16000
	s_add_u32 s18, s18, 0x2000
	s_addc_u32 s19, s19, 0
	global_load_lds_dwordx4 v11, s[18:19]
	s_waitcnt lgkmcnt(8)
	v_mfma_f32_32x32x16_bf16 v[192:207], v[248:251], v[128:131], v[80:95]
	ds_read_b128 v[248:251], v6 offset:40960
	s_mov_b64 s[18:19], 0
	v_max3_f32 v190, v96, v97, v98
	v_max3_f32 v190, v190, v99, v100
	v_max3_f32 v190, v190, v101, v102
	v_max3_f32 v190, v190, v103, v104
	v_mfma_f32_32x32x16_bf16 v[208:223], v[252:255], v[128:131], v[80:95]
	ds_read_b128 v[252:255], v6 offset:45056
	v_max3_f32 v190, v190, v105, v106
	v_max3_f32 v190, v190, v107, v108
	v_max3_f32 v190, v190, v109, v110
	v_max3_f32 v190, v190, v111, v111
	v_max3_f32 v191, v112, v113, v114
	v_max3_f32 v191, v191, v115, v116
	s_waitcnt lgkmcnt(8)
	v_mfma_f32_32x32x16_bf16 v[192:207], v[160:163], v[132:135], v[192:207]
	ds_read_b128 v[160:163], v7 offset:32768
	v_max3_f32 v191, v191, v117, v118
	v_max3_f32 v191, v191, v119, v120
	v_max3_f32 v191, v191, v121, v122
	v_max3_f32 v191, v191, v123, v124
	v_max3_f32 v191, v191, v125, v126
	v_max3_f32 v191, v191, v127, v127
	v_mfma_f32_32x32x16_bf16 v[208:223], v[164:167], v[132:135], v[208:223]
	ds_read_b128 v[164:167], v7 offset:36864
	v_max_f32_e32 v0, v190, v191
	s_nop 0
	v_cmp_lt_f32_e32 vcc, s67, v0
	s_cbranch_vccnz .Lfa_rareA_1
.Lfa_retA_1:
	s_waitcnt lgkmcnt(8)
	v_mfma_f32_32x32x16_bf16 v[192:207], v[168:171], v[136:139], v[192:207]
	ds_read_b128 v[168:171], v7 offset:40960
	v_exp_f32_e32 v96, v96
	v_exp_f32_e32 v97, v97
	v_exp_f32_e32 v98, v98
	v_exp_f32_e32 v99, v99
	v_exp_f32_e32 v100, v100
	v_mfma_f32_32x32x16_bf16 v[208:223], v[224:227], v[136:139], v[208:223]
	ds_read_b128 v[224:227], v7 offset:45056
	v_exp_f32_e32 v101, v101
	v_exp_f32_e32 v102, v102
	v_exp_f32_e32 v103, v103
	v_add_f32_e32 v159, v159, v96
	v_add_f32_e32 v159, v159, v97
	s_waitcnt lgkmcnt(8)
	v_mfma_f32_32x32x16_bf16 v[192:207], v[228:231], v[140:143], v[192:207]
	ds_read_b128 v[228:231], v8 offset:32768
	v_add_f32_e32 v159, v159, v98
	v_add_f32_e32 v159, v159, v99
	v_cvt_pk_bf16_f32 v96, v96, v97
	v_cvt_pk_bf16_f32 v97, v98, v99
	v_add_f32_e32 v159, v159, v100
	v_mfma_f32_32x32x16_bf16 v[208:223], v[232:235], v[140:143], v[208:223]
	ds_read_b128 v[232:235], v8 offset:36864
	v_add_f32_e32 v159, v159, v101
	v_cvt_pk_bf16_f32 v98, v100, v101
	v_cvt_pk_bf16_f32 v99, v102, v103
	v_add_f32_e32 v159, v159, v102
	v_add_f32_e32 v159, v159, v103
	s_waitcnt lgkmcnt(8)
	v_mfma_f32_32x32x16_bf16 v[64:79], v[236:239], v[96:99], v[64:79]
	ds_read_b128 v[236:239], v8 offset:40960
	v_exp_f32_e32 v104, v104
	v_exp_f32_e32 v105, v105
	v_exp_f32_e32 v106, v106
	v_exp_f32_e32 v107, v107
	v_exp_f32_e32 v108, v108
	v_mfma_f32_32x32x16_bf16 v[48:63], v[244:247], v[96:99], v[48:63]
	ds_read_b128 v[244:247], v8 offset:45056
	v_exp_f32_e32 v109, v109
	v_exp_f32_e32 v110, v110
	v_exp_f32_e32 v111, v111
	v_add_f32_e32 v159, v159, v104
	v_add_f32_e32 v159, v159, v105
	s_waitcnt lgkmcnt(8)
	v_mfma_f32_32x32x16_bf16 v[32:47], v[248:251], v[96:99], v[32:47]
	ds_read_b128 v[248:251], v9 offset:32768
	v_add_f32_e32 v159, v159, v106
	v_add_f32_e32 v159, v159, v107
	v_cvt_pk_bf16_f32 v104, v104, v105
	v_cvt_pk_bf16_f32 v105, v106, v107
	v_add_f32_e32 v159, v159, v108
	v_mfma_f32_32x32x16_bf16 v[16:31], v[252:255], v[96:99], v[16:31]
	ds_read_b128 v[252:255], v9 offset:36864
	v_add_f32_e32 v159, v159, v109
	v_cvt_pk_bf16_f32 v106, v108, v109
	v_cvt_pk_bf16_f32 v107, v110, v111
	v_add_f32_e32 v159, v159, v110
	v_add_f32_e32 v159, v159, v111
	s_waitcnt lgkmcnt(8)
	v_mfma_f32_32x32x16_bf16 v[64:79], v[160:163], v[104:107], v[64:79]
	ds_read_b128 v[160:163], v9 offset:40960
	v_exp_f32_e32 v112, v112
	v_exp_f32_e32 v113, v113
	v_exp_f32_e32 v114, v114
	v_exp_f32_e32 v115, v115
	v_exp_f32_e32 v116, v116
	v_mfma_f32_32x32x16_bf16 v[48:63], v[164:167], v[104:107], v[48:63]
	ds_read_b128 v[164:167], v9 offset:45056
	v_exp_f32_e32 v117, v117
	v_exp_f32_e32 v118, v118
	v_exp_f32_e32 v119, v119
	v_add_f32_e32 v159, v159, v112
	v_add_f32_e32 v159, v159, v113
	s_waitcnt lgkmcnt(8)
	v_mfma_f32_32x32x16_bf16 v[32:47], v[168:171], v[104:107], v[32:47]
	ds_read_b128 v[168:171], v6 offset:49152
	v_add_f32_e32 v159, v159, v114
	v_add_f32_e32 v159, v159, v115
	v_cvt_pk_bf16_f32 v112, v112, v113
	v_cvt_pk_bf16_f32 v113, v114, v115
	v_add_f32_e32 v159, v159, v116
	v_mfma_f32_32x32x16_bf16 v[16:31], v[224:227], v[104:107], v[16:31]
	ds_read_b128 v[224:227], v6 offset:53248
	v_add_f32_e32 v159, v159, v117
	v_cvt_pk_bf16_f32 v114, v116, v117
	v_cvt_pk_bf16_f32 v115, v118, v119
	v_add_f32_e32 v159, v159, v118
	v_add_f32_e32 v159, v159, v119
	s_waitcnt lgkmcnt(8)
	v_mfma_f32_32x32x16_bf16 v[64:79], v[228:231], v[112:115], v[64:79]
	ds_read_b128 v[228:231], v6 offset:57344
	v_exp_f32_e32 v120, v120
	v_exp_f32_e32 v121, v121
	v_exp_f32_e32 v122, v122
	v_exp_f32_e32 v123, v123
	v_exp_f32_e32 v124, v124
	v_max3_f32 v190, v192, v193, v194
	v_max3_f32 v190, v190, v195, v196
	v_max3_f32 v190, v190, v197, v198
	v_max3_f32 v190, v190, v199, v200
	v_mfma_f32_32x32x16_bf16 v[48:63], v[232:235], v[112:115], v[48:63]
	ds_read_b128 v[232:235], v6 offset:61440
	v_exp_f32_e32 v125, v125
	v_exp_f32_e32 v126, v126
	v_exp_f32_e32 v127, v127
	v_add_f32_e32 v159, v159, v120
	v_add_f32_e32 v159, v159, v121
	v_max3_f32 v190, v190, v201, v202
	v_max3_f32 v190, v190, v203, v204
	v_max3_f32 v190, v190, v205, v206
	v_max3_f32 v190, v190, v207, v207
	s_waitcnt lgkmcnt(8)
	v_mfma_f32_32x32x16_bf16 v[32:47], v[236:239], v[112:115], v[32:47]
	ds_read_b128 v[236:239], v7 offset:49152
	v_add_f32_e32 v159, v159, v122
	v_add_f32_e32 v159, v159, v123
	v_cvt_pk_bf16_f32 v120, v120, v121
	v_cvt_pk_bf16_f32 v121, v122, v123
	v_add_f32_e32 v159, v159, v124
	v_max3_f32 v191, v208, v209, v210
	v_max3_f32 v191, v191, v211, v212
	v_max3_f32 v191, v191, v213, v214
	v_max3_f32 v191, v191, v215, v216
	v_mfma_f32_32x32x16_bf16 v[16:31], v[244:247], v[112:115], v[16:31]
	ds_read_b128 v[244:247], v7 offset:53248
	v_add_f32_e32 v159, v159, v125
	v_cvt_pk_bf16_f32 v122, v124, v125
	v_cvt_pk_bf16_f32 v123, v126, v127
	v_add_f32_e32 v159, v159, v126
	v_add_f32_e32 v159, v159, v127
	v_max3_f32 v191, v191, v217, v218
	v_max3_f32 v191, v191, v219, v220
	v_max3_f32 v191, v191, v221, v222
	v_max3_f32 v191, v191, v223, v223
	s_waitcnt lgkmcnt(8)
	v_mfma_f32_32x32x16_bf16 v[64:79], v[248:251], v[120:123], v[64:79]
	ds_read_b128 v[248:251], v7 offset:57344
	v_max_f32_e32 v0, v190, v191
	s_nop 0
	v_cmp_lt_f32_e32 vcc, s67, v0
	s_or_b64 vcc, vcc, s[18:19]
	s_cbranch_vccnz .Lfa_rareB_1
.Lfa_retB_1:
	v_exp_f32_e32 v192, v192
	v_exp_f32_e32 v193, v193
	v_exp_f32_e32 v194, v194
	v_exp_f32_e32 v195, v195
	v_exp_f32_e32 v196, v196
	v_mfma_f32_32x32x16_bf16 v[48:63], v[252:255], v[120:123], v[48:63]
	ds_read_b128 v[252:255], v7 offset:61440
	v_exp_f32_e32 v197, v197
	v_exp_f32_e32 v198, v198
	v_exp_f32_e32 v199, v199
	v_add_f32_e32 v159, v159, v192
	v_add_f32_e32 v159, v159, v193
	s_waitcnt lgkmcnt(8)
	v_mfma_f32_32x32x16_bf16 v[32:47], v[160:163], v[120:123], v[32:47]
	ds_read_b128 v[160:163], v8 offset:49152
	v_add_f32_e32 v159, v159, v194
	v_add_f32_e32 v159, v159, v195
	v_cvt_pk_bf16_f32 v192, v192, v193
	v_cvt_pk_bf16_f32 v193, v194, v195
	v_add_f32_e32 v159, v159, v196
	v_mfma_f32_32x32x16_bf16 v[16:31], v[164:167], v[120:123], v[16:31]
	ds_read_b128 v[164:167], v8 offset:53248
	v_add_f32_e32 v159, v159, v197
	v_cvt_pk_bf16_f32 v194, v196, v197
	v_cvt_pk_bf16_f32 v195, v198, v199
	v_add_f32_e32 v159, v159, v198
	v_add_f32_e32 v159, v159, v199
	s_cmp_lg_u32 s80, 0
	s_cbranch_scc1 .Lfa_fixO_1
.Lfa_retO_1:
	s_waitcnt lgkmcnt(8)
	v_mfma_f32_32x32x16_bf16 v[64:79], v[168:171], v[192:195], v[64:79]
	ds_read_b128 v[168:171], v8 offset:57344
	v_exp_f32_e32 v200, v200
	v_exp_f32_e32 v201, v201
	v_exp_f32_e32 v202, v202
	v_exp_f32_e32 v203, v203
	v_exp_f32_e32 v204, v204
	v_mfma_f32_32x32x16_bf16 v[48:63], v[224:227], v[192:195], v[48:63]
	ds_read_b128 v[224:227], v8 offset:61440
	v_exp_f32_e32 v205, v205
	v_exp_f32_e32 v206, v206
	v_exp_f32_e32 v207, v207
	v_add_f32_e32 v159, v159, v200
	v_add_f32_e32 v159, v159, v201
	s_waitcnt lgkmcnt(8)
	v_mfma_f32_32x32x16_bf16 v[32:47], v[228:231], v[192:195], v[32:47]
	ds_read_b128 v[228:231], v9 offset:49152
	v_add_f32_e32 v159, v159, v202
	v_add_f32_e32 v159, v159, v203
	v_cvt_pk_bf16_f32 v200, v200, v201
	v_cvt_pk_bf16_f32 v201, v202, v203
	v_add_f32_e32 v159, v159, v204
	v_mfma_f32_32x32x16_bf16 v[16:31], v[232:235], v[192:195], v[16:31]
	ds_read_b128 v[232:235], v9 offset:53248
	v_add_f32_e32 v159, v159, v205
	v_cvt_pk_bf16_f32 v202, v204, v205
	v_cvt_pk_bf16_f32 v203, v206, v207
	v_add_f32_e32 v159, v159, v206
	v_add_f32_e32 v159, v159, v207
	s_waitcnt lgkmcnt(8)
	v_mfma_f32_32x32x16_bf16 v[64:79], v[236:239], v[200:203], v[64:79]
	ds_read_b128 v[236:239], v9 offset:57344
	v_exp_f32_e32 v208, v208
	v_exp_f32_e32 v209, v209
	v_exp_f32_e32 v210, v210
	v_exp_f32_e32 v211, v211
	v_exp_f32_e32 v212, v212
	v_mfma_f32_32x32x16_bf16 v[48:63], v[244:247], v[200:203], v[48:63]
	ds_read_b128 v[244:247], v9 offset:61440
	v_exp_f32_e32 v213, v213
	v_exp_f32_e32 v214, v214
	v_exp_f32_e32 v215, v215
	v_add_f32_e32 v159, v159, v208
	v_add_f32_e32 v159, v159, v209
	s_waitcnt lgkmcnt(8)
	v_mfma_f32_32x32x16_bf16 v[32:47], v[248:251], v[200:203], v[32:47]
	v_add_f32_e32 v159, v159, v210
	v_add_f32_e32 v159, v159, v211
	v_cvt_pk_bf16_f32 v208, v208, v209
	v_cvt_pk_bf16_f32 v209, v210, v211
	v_add_f32_e32 v159, v159, v212
	v_mfma_f32_32x32x16_bf16 v[16:31], v[252:255], v[200:203], v[16:31]
	v_add_f32_e32 v159, v159, v213
	v_cvt_pk_bf16_f32 v210, v212, v213
	v_cvt_pk_bf16_f32 v211, v214, v215
	v_add_f32_e32 v159, v159, v214
	v_add_f32_e32 v159, v159, v215
	s_waitcnt lgkmcnt(6)
	v_mfma_f32_32x32x16_bf16 v[64:79], v[160:163], v[208:211], v[64:79]
	v_exp_f32_e32 v216, v216
	v_exp_f32_e32 v217, v217
	v_exp_f32_e32 v218, v218
	v_exp_f32_e32 v219, v219
	v_exp_f32_e32 v220, v220
	v_mfma_f32_32x32x16_bf16 v[48:63], v[164:167], v[208:211], v[48:63]
	v_exp_f32_e32 v221, v221
	v_exp_f32_e32 v222, v222
	v_exp_f32_e32 v223, v223
	v_add_f32_e32 v159, v159, v216
	v_add_f32_e32 v159, v159, v217
	s_waitcnt lgkmcnt(4)
	v_mfma_f32_32x32x16_bf16 v[32:47], v[168:171], v[208:211], v[32:47]
	v_add_f32_e32 v159, v159, v218
	v_add_f32_e32 v159, v159, v219
	v_cvt_pk_bf16_f32 v216, v216, v217
	v_cvt_pk_bf16_f32 v217, v218, v219
	v_add_f32_e32 v159, v159, v220
	v_mfma_f32_32x32x16_bf16 v[16:31], v[224:227], v[208:211], v[16:31]
	v_add_f32_e32 v159, v159, v221
	v_cvt_pk_bf16_f32 v218, v220, v221
	v_cvt_pk_bf16_f32 v219, v222, v223
	v_add_f32_e32 v159, v159, v222
	v_add_f32_e32 v159, v159, v223
	s_waitcnt lgkmcnt(2)
	v_mfma_f32_32x32x16_bf16 v[64:79], v[228:231], v[216:219], v[64:79]
	s_add_i32 s26, s26, 1
	s_add_u32 s6, s6, 0x8000
	v_mfma_f32_32x32x16_bf16 v[48:63], v[232:235], v[216:219], v[48:63]
	s_addc_u32 s7, s7, 0
	s_addk_i32 s8, 0x80
	s_waitcnt lgkmcnt(0)
	v_mfma_f32_32x32x16_bf16 v[32:47], v[236:239], v[216:219], v[32:47]
	v_add_u32_e32 v158, 0xffffff80, v158
	v_mfma_f32_32x32x16_bf16 v[16:31], v[244:247], v[216:219], v[16:31]
	s_cmp_lt_i32 s26, s5
	s_cbranch_scc0 .Lfa_exit
.Lfa_top_0:
	s_waitcnt vmcnt(0) lgkmcnt(0)
	s_barrier
	ds_read_b128 v[160:163], v2
	ds_read_b128 v[164:167], v2 offset:8192
	ds_read_b128 v[168:171], v3
	ds_read_b128 v[224:227], v3 offset:8192
	ds_read_b128 v[228:231], v4
	ds_read_b128 v[232:235], v4 offset:8192
	ds_read_b128 v[236:239], v5
	ds_read_b128 v[244:247], v5 offset:8192
	ds_read_b128 v[248:251], v2 offset:16384
	ds_read_b128 v[252:255], v2 offset:24576
	s_mov_b32 s80, 0
	s_waitcnt lgkmcnt(8)
	v_mfma_f32_32x32x16_bf16 v[96:111], v[160:163], v[128:131], v[80:95]
	ds_read_b128 v[160:163], v3 offset:16384
	s_sub_i32 s16, s8, 64
	s_mov_b32 s17, 0
	s_lshl_b64 s[16:17], s[16:17], 11
	s_add_u32 s16, s16, s86
	s_addc_u32 s17, s17, s87
	s_add_u32 s18, s76, s6
	s_addc_u32 s19, s77, s7
	s_add_u32 s18, s18, 0x6d08000
	s_addc_u32 s19, s19, 0
	s_add_i32 m0, s24, 0x8000
	s_nop 0
	global_load_lds_dwordx4 v10, s[16:17]
	v_mfma_f32_32x32x16_bf16 v[112:127], v[164:167], v[128:131], v[80:95]
	ds_read_b128 v[164:167], v3 offset:24576
	s_add_i32 m0, s24, 0xa000
	s_add_u32 s16, s16, 0x10000
	s_addc_u32 s17, s17, 0
	global_load_lds_dwordx4 v10, s[16:17]
	s_waitcnt lgkmcnt(8)
	v_mfma_f32_32x32x16_bf16 v[96:111], v[168:171], v[132:135], v[96:111]
	ds_read_b128 v[168:171], v4 offset:16384
	s_add_i32 m0, s24, 0x18000
	s_nop 0
	global_load_lds_dwordx4 v11, s[18:19]
	v_mfma_f32_32x32x16_bf16 v[112:127], v[224:227], v[132:135], v[112:127]
	ds_read_b128 v[224:227], v4 offset:24576
	s_add_i32 m0, s24, 0x1a000
	s_add_u32 s18, s18, 0x2000
	s_addc_u32 s19, s19, 0
	global_load_lds_dwordx4 v11, s[18:19]
	s_waitcnt lgkmcnt(8)
	v_mfma_f32_32x32x16_bf16 v[96:111], v[228:231], v[136:139], v[96:111]
	ds_read_b128 v[228:231], v5 offset:16384
	s_add_i32 m0, s24, 0xc000
	s_add_u32 s16, s16, 0x10000
	s_addc_u32 s17, s17, 0
	global_load_lds_dwordx4 v10, s[16:17]
	v_mfma_f32_32x32x16_bf16 v[112:127], v[232:235], v[136:139], v[112:127]
	ds_read_b128 v[232:235], v5 offset:24576
	s_add_i32 m0, s24, 0xe000
	s_add_u32 s16, s16, 0x10000
	s_addc_u32 s17, s17, 0
	global_load_lds_dwordx4 v10, s[16:17]
	s_waitcnt lgkmcnt(8)
	v_mfma_f32_32x32x16_bf16 v[96:111], v[236:239], v[140:143], v[96:111]
	ds_read_b128 v[236:239], v6
	s_add_i32 m0, s24, 0x1c000
	s_add_u32 s18, s18, 0x2000
	s_addc_u32 s19, s19, 0
	global_load_lds_dwordx4 v11, s[18:19]
	v_mfma_f32_32x32x16_bf16 v[112:127], v[244:247], v[140:143], v[112:127]
	ds_read_b128 v[244:247], v6 offset:4096
	s_add_i32 m0, s24, 0x1e000
	s_add_u32 s18, s18, 0x2000
	s_addc_u32 s19, s19, 0
	global_load_lds_dwordx4 v11, s[18:19]
	s_waitcnt lgkmcnt(8)
	v_mfma_f32_32x32x16_bf16 v[192:207], v[248:251], v[128:131], v[80:95]
	ds_read_b128 v[248:251], v6 offset:8192
	s_mov_b64 s[18:19], 0
	v_max3_f32 v190, v96, v97, v98
	v_max3_f32 v190, v190, v99, v100
	v_max3_f32 v190, v190, v101, v102
	v_max3_f32 v190, v190, v103, v104
	v_mfma_f32_32x32x16_bf16 v[208:223], v[252:255], v[128:131], v[80:95]
	ds_read_b128 v[252:255], v6 offset:12288
	v_max3_f32 v190, v190, v105, v106
	v_max3_f32 v190, v190, v107, v108
	v_max3_f32 v190, v190, v109, v110
	v_max3_f32 v190, v190, v111, v111
	v_max3_f32 v191, v112, v113, v114
	v_max3_f32 v191, v191, v115, v116
	s_waitcnt lgkmcnt(8)
	v_mfma_f32_32x32x16_bf16 v[192:207], v[160:163], v[132:135], v[192:207]
	ds_read_b128 v[160:163], v7
	v_max3_f32 v191, v191, v117, v118
	v_max3_f32 v191, v191, v119, v120
	v_max3_f32 v191, v191, v121, v122
	v_max3_f32 v191, v191, v123, v124
	v_max3_f32 v191, v191, v125, v126
	v_max3_f32 v191, v191, v127, v127
	v_mfma_f32_32x32x16_bf16 v[208:223], v[164:167], v[132:135], v[208:223]
	ds_read_b128 v[164:167], v7 offset:4096
	v_max_f32_e32 v0, v190, v191
	s_nop 0
	v_cmp_lt_f32_e32 vcc, s67, v0
	s_cbranch_vccnz .Lfa_rareA_0
.Lfa_retA_0:
	s_waitcnt lgkmcnt(8)
	v_mfma_f32_32x32x16_bf16 v[192:207], v[168:171], v[136:139], v[192:207]
	ds_read_b128 v[168:171], v7 offset:8192
	v_exp_f32_e32 v96, v96
	v_exp_f32_e32 v97, v97
	v_exp_f32_e32 v98, v98
	v_exp_f32_e32 v99, v99
	v_exp_f32_e32 v100, v100
	v_mfma_f32_32x32x16_bf16 v[208:223], v[224:227], v[136:139], v[208:223]
	ds_read_b128 v[224:227], v7 offset:12288
	v_exp_f32_e32 v101, v101
	v_exp_f32_e32 v102, v102
	v_exp_f32_e32 v103, v103
	v_add_f32_e32 v159, v159, v96
	v_add_f32_e32 v159, v159, v97
	s_waitcnt lgkmcnt(8)
	v_mfma_f32_32x32x16_bf16 v[192:207], v[228:231], v[140:143], v[192:207]
	ds_read_b128 v[228:231], v8
	v_add_f32_e32 v159, v159, v98
	v_add_f32_e32 v159, v159, v99
	v_cvt_pk_bf16_f32 v96, v96, v97
	v_cvt_pk_bf16_f32 v97, v98, v99
	v_add_f32_e32 v159, v159, v100
	v_mfma_f32_32x32x16_bf16 v[208:223], v[232:235], v[140:143], v[208:223]
	ds_read_b128 v[232:235], v8 offset:4096
	v_add_f32_e32 v159, v159, v101
	v_cvt_pk_bf16_f32 v98, v100, v101
	v_cvt_pk_bf16_f32 v99, v102, v103
	v_add_f32_e32 v159, v159, v102
	v_add_f32_e32 v159, v159, v103
	s_waitcnt lgkmcnt(8)
	v_mfma_f32_32x32x16_bf16 v[64:79], v[236:239], v[96:99], v[64:79]
	ds_read_b128 v[236:239], v8 offset:8192
	v_exp_f32_e32 v104, v104
	v_exp_f32_e32 v105, v105
	v_exp_f32_e32 v106, v106
	v_exp_f32_e32 v107, v107
	v_exp_f32_e32 v108, v108
	v_mfma_f32_32x32x16_bf16 v[48:63], v[244:247], v[96:99], v[48:63]
	ds_read_b128 v[244:247], v8 offset:12288
	v_exp_f32_e32 v109, v109
	v_exp_f32_e32 v110, v110
	v_exp_f32_e32 v111, v111
	v_add_f32_e32 v159, v159, v104
	v_add_f32_e32 v159, v159, v105
	s_waitcnt lgkmcnt(8)
	v_mfma_f32_32x32x16_bf16 v[32:47], v[248:251], v[96:99], v[32:47]
	ds_read_b128 v[248:251], v9
	v_add_f32_e32 v159, v159, v106
	v_add_f32_e32 v159, v159, v107
	v_cvt_pk_bf16_f32 v104, v104, v105
	v_cvt_pk_bf16_f32 v105, v106, v107
	v_add_f32_e32 v159, v159, v108
	v_mfma_f32_32x32x16_bf16 v[16:31], v[252:255], v[96:99], v[16:31]
	ds_read_b128 v[252:255], v9 offset:4096
	v_add_f32_e32 v159, v159, v109
	v_cvt_pk_bf16_f32 v106, v108, v109
	v_cvt_pk_bf16_f32 v107, v110, v111
	v_add_f32_e32 v159, v159, v110
	v_add_f32_e32 v159, v159, v111
	s_waitcnt lgkmcnt(8)
	v_mfma_f32_32x32x16_bf16 v[64:79], v[160:163], v[104:107], v[64:79]
	ds_read_b128 v[160:163], v9 offset:8192
	v_exp_f32_e32 v112, v112
	v_exp_f32_e32 v113, v113
	v_exp_f32_e32 v114, v114
	v_exp_f32_e32 v115, v115
	v_exp_f32_e32 v116, v116
	v_mfma_f32_32x32x16_bf16 v[48:63], v[164:167], v[104:107], v[48:63]
	ds_read_b128 v[164:167], v9 offset:12288
	v_exp_f32_e32 v117, v117
	v_exp_f32_e32 v118, v118
	v_exp_f32_e32 v119, v119
	v_add_f32_e32 v159, v159, v112
	v_add_f32_e32 v159, v159, v113
	s_waitcnt lgkmcnt(8)
	v_mfma_f32_32x32x16_bf16 v[32:47], v[168:171], v[104:107], v[32:47]
	ds_read_b128 v[168:171], v6 offset:16384
	v_add_f32_e32 v159, v159, v114
	v_add_f32_e32 v159, v159, v115
	v_cvt_pk_bf16_f32 v112, v112, v113
	v_cvt_pk_bf16_f32 v113, v114, v115
	v_add_f32_e32 v159, v159, v116
	v_mfma_f32_32x32x16_bf16 v[16:31], v[224:227], v[104:107], v[16:31]
	ds_read_b128 v[224:227], v6 offset:20480
	v_add_f32_e32 v159, v159, v117
	v_cvt_pk_bf16_f32 v114, v116, v117
	v_cvt_pk_bf16_f32 v115, v118, v119
	v_add_f32_e32 v159, v159, v118
	v_add_f32_e32 v159, v159, v119
	s_waitcnt lgkmcnt(8)
	v_mfma_f32_32x32x16_bf16 v[64:79], v[228:231], v[112:115], v[64:79]
	ds_read_b128 v[228:231], v6 offset:24576
	v_exp_f32_e32 v120, v120
	v_exp_f32_e32 v121, v121
	v_exp_f32_e32 v122, v122
	v_exp_f32_e32 v123, v123
	v_exp_f32_e32 v124, v124
	v_max3_f32 v190, v192, v193, v194
	v_max3_f32 v190, v190, v195, v196
	v_max3_f32 v190, v190, v197, v198
	v_max3_f32 v190, v190, v199, v200
	v_mfma_f32_32x32x16_bf16 v[48:63], v[232:235], v[112:115], v[48:63]
	ds_read_b128 v[232:235], v6 offset:28672
	v_exp_f32_e32 v125, v125
	v_exp_f32_e32 v126, v126
	v_exp_f32_e32 v127, v127
	v_add_f32_e32 v159, v159, v120
	v_add_f32_e32 v159, v159, v121
	v_max3_f32 v190, v190, v201, v202
	v_max3_f32 v190, v190, v203, v204
	v_max3_f32 v190, v190, v205, v206
	v_max3_f32 v190, v190, v207, v207
	s_waitcnt lgkmcnt(8)
	v_mfma_f32_32x32x16_bf16 v[32:47], v[236:239], v[112:115], v[32:47]
	ds_read_b128 v[236:239], v7 offset:16384
	v_add_f32_e32 v159, v159, v122
	v_add_f32_e32 v159, v159, v123
	v_cvt_pk_bf16_f32 v120, v120, v121
	v_cvt_pk_bf16_f32 v121, v122, v123
	v_add_f32_e32 v159, v159, v124
	v_max3_f32 v191, v208, v209, v210
	v_max3_f32 v191, v191, v211, v212
	v_max3_f32 v191, v191, v213, v214
	v_max3_f32 v191, v191, v215, v216
	v_mfma_f32_32x32x16_bf16 v[16:31], v[244:247], v[112:115], v[16:31]
	ds_read_b128 v[244:247], v7 offset:20480
	v_add_f32_e32 v159, v159, v125
	v_cvt_pk_bf16_f32 v122, v124, v125
	v_cvt_pk_bf16_f32 v123, v126, v127
	v_add_f32_e32 v159, v159, v126
	v_add_f32_e32 v159, v159, v127
	v_max3_f32 v191, v191, v217, v218
	v_max3_f32 v191, v191, v219, v220
	v_max3_f32 v191, v191, v221, v222
	v_max3_f32 v191, v191, v223, v223
	s_waitcnt lgkmcnt(8)
	v_mfma_f32_32x32x16_bf16 v[64:79], v[248:251], v[120:123], v[64:79]
	ds_read_b128 v[248:251], v7 offset:24576
	v_max_f32_e32 v0, v190, v191
	s_nop 0
	v_cmp_lt_f32_e32 vcc, s67, v0
	s_or_b64 vcc, vcc, s[18:19]
	s_cbranch_vccnz .Lfa_rareB_0

.Lfa_retO_0:
	s_waitcnt lgkmcnt(8)
	v_mfma_f32_32x32x16_bf16 v[64:79], v[168:171], v[192:195], v[64:79]
	ds_read_b128 v[168:171], v8 offset:24576
	v_exp_f32_e32 v200, v200
	v_exp_f32_e32 v201, v201
	v_exp_f32_e32 v202, v202
	v_exp_f32_e32 v203, v203
	v_exp_f32_e32 v204, v204
	v_mfma_f32_32x32x16_bf16 v[48:63], v[224:227], v[192:195], v[48:63]
	ds_read_b128 v[224:227], v8 offset:28672
	v_exp_f32_e32 v205, v205
	v_exp_f32_e32 v206, v206
	v_exp_f32_e32 v207, v207
	v_add_f32_e32 v159, v159, v200
	v_add_f32_e32 v159, v159, v201
	s_waitcnt lgkmcnt(8)
	v_mfma_f32_32x32x16_bf16 v[32:47], v[228:231], v[192:195], v[32:47]
	ds_read_b128 v[228:231], v9 offset:16384
	v_add_f32_e32 v159, v159, v202
	v_add_f32_e32 v159, v159, v203
	v_cvt_pk_bf16_f32 v200, v200, v201
	v_cvt_pk_bf16_f32 v201, v202, v203
	v_add_f32_e32 v159, v159, v204
	v_mfma_f32_32x32x16_bf16 v[16:31], v[232:235], v[192:195], v[16:31]
	ds_read_b128 v[232:235], v9 offset:20480
	v_add_f32_e32 v159, v159, v205
	v_cvt_pk_bf16_f32 v202, v204, v205
	v_cvt_pk_bf16_f32 v203, v206, v207
	v_add_f32_e32 v159, v159, v206
	v_add_f32_e32 v159, v159, v207
	s_waitcnt lgkmcnt(8)
	v_mfma_f32_32x32x16_bf16 v[64:79], v[236:239], v[200:203], v[64:79]
	ds_read_b128 v[236:239], v9 offset:24576
	v_exp_f32_e32 v208, v208
	v_exp_f32_e32 v209, v209
	v_exp_f32_e32 v210, v210
	v_exp_f32_e32 v211, v211
	v_exp_f32_e32 v212, v212
	v_mfma_f32_32x32x16_bf16 v[48:63], v[244:247], v[200:203], v[48:63]
	ds_read_b128 v[244:247], v9 offset:28672
	v_exp_f32_e32 v213, v213
	v_exp_f32_e32 v214, v214
	v_exp_f32_e32 v215, v215
	v_add_f32_e32 v159, v159, v208
	v_add_f32_e32 v159, v159, v209
	s_waitcnt lgkmcnt(8)
	v_mfma_f32_32x32x16_bf16 v[32:47], v[248:251], v[200:203], v[32:47]
	v_add_f32_e32 v159, v159, v210
	v_add_f32_e32 v159, v159, v211
	v_cvt_pk_bf16_f32 v208, v208, v209
	v_cvt_pk_bf16_f32 v209, v210, v211
	v_add_f32_e32 v159, v159, v212
	v_mfma_f32_32x32x16_bf16 v[16:31], v[252:255], v[200:203], v[16:31]
	v_add_f32_e32 v159, v159, v213
	v_cvt_pk_bf16_f32 v210, v212, v213
	v_cvt_pk_bf16_f32 v211, v214, v215
	v_add_f32_e32 v159, v159, v214
	v_add_f32_e32 v159, v159, v215
	s_waitcnt lgkmcnt(6)
	v_mfma_f32_32x32x16_bf16 v[64:79], v[160:163], v[208:211], v[64:79]
	v_exp_f32_e32 v216, v216
	v_exp_f32_e32 v217, v217
	v_exp_f32_e32 v218, v218
	v_exp_f32_e32 v219, v219
	v_exp_f32_e32 v220, v220
	v_mfma_f32_32x32x16_bf16 v[48:63], v[164:167], v[208:211], v[48:63]
	v_exp_f32_e32 v221, v221
	v_exp_f32_e32 v222, v222
	v_exp_f32_e32 v223, v223
	v_add_f32_e32 v159, v159, v216
	v_add_f32_e32 v159, v159, v217
	s_waitcnt lgkmcnt(4)
	v_mfma_f32_32x32x16_bf16 v[32:47], v[168:171], v[208:211], v[32:47]
	v_add_f32_e32 v159, v159, v218
	v_add_f32_e32 v159, v159, v219
	v_cvt_pk_bf16_f32 v216, v216, v217
	v_cvt_pk_bf16_f32 v217, v218, v219
	v_add_f32_e32 v159, v159, v220
	v_mfma_f32_32x32x16_bf16 v[16:31], v[224:227], v[208:211], v[16:31]
	v_add_f32_e32 v159, v159, v221
	v_cvt_pk_bf16_f32 v218, v220, v221
	v_cvt_pk_bf16_f32 v219, v222, v223
	v_add_f32_e32 v159, v159, v222
	v_add_f32_e32 v159, v159, v223
	s_waitcnt lgkmcnt(2)
	v_mfma_f32_32x32x16_bf16 v[64:79], v[228:231], v[216:219], v[64:79]
	s_add_i32 s26, s26, 1
	s_add_u32 s6, s6, 0x8000
	v_mfma_f32_32x32x16_bf16 v[48:63], v[232:235], v[216:219], v[48:63]
	s_addc_u32 s7, s7, 0
	s_addk_i32 s8, 0x80
	s_waitcnt lgkmcnt(0)
	v_mfma_f32_32x32x16_bf16 v[32:47], v[236:239], v[216:219], v[32:47]
	v_add_u32_e32 v158, 0xffffff80, v158
	v_mfma_f32_32x32x16_bf16 v[16:31], v[244:247], v[216:219], v[16:31]
	s_cmp_lt_i32 s26, s5
	s_cbranch_scc1 .Lfa_top_1

.Lfa_rareA_1:
	s_nop 7
	v_mov_b32_e32 v15, v0
	s_nop 1
	v_permlane32_swap_b32_e32 v0, v15
	v_max_f32_e32 v0, v0, v15
	v_max_f32_e32 v0, v0, v0
	v_max_f32_e32 v0, 0, v0
	v_exp_f32_e64 v15, -v0
	v_sub_f32_e32 v96, v96, v0
	v_sub_f32_e32 v97, v97, v0
	v_sub_f32_e32 v98, v98, v0
	v_sub_f32_e32 v99, v99, v0
	v_sub_f32_e32 v100, v100, v0
	v_sub_f32_e32 v101, v101, v0
	v_sub_f32_e32 v102, v102, v0
	v_sub_f32_e32 v103, v103, v0
	v_sub_f32_e32 v104, v104, v0
	v_sub_f32_e32 v105, v105, v0
	v_sub_f32_e32 v106, v106, v0
	v_sub_f32_e32 v107, v107, v0
	v_sub_f32_e32 v108, v108, v0
	v_sub_f32_e32 v109, v109, v0
	v_sub_f32_e32 v110, v110, v0
	v_sub_f32_e32 v111, v111, v0
	v_sub_f32_e32 v112, v112, v0
	v_sub_f32_e32 v113, v113, v0
	v_sub_f32_e32 v114, v114, v0
	v_sub_f32_e32 v115, v115, v0
	v_sub_f32_e32 v116, v116, v0
	v_sub_f32_e32 v117, v117, v0
	v_sub_f32_e32 v118, v118, v0
	v_sub_f32_e32 v119, v119, v0
	v_sub_f32_e32 v120, v120, v0
	v_sub_f32_e32 v121, v121, v0
	v_sub_f32_e32 v122, v122, v0
	v_sub_f32_e32 v123, v123, v0
	v_sub_f32_e32 v124, v124, v0
	v_sub_f32_e32 v125, v125, v0
	v_sub_f32_e32 v126, v126, v0
	v_sub_f32_e32 v127, v127, v0
	v_sub_f32_e32 v80, v80, v0
	v_sub_f32_e32 v81, v81, v0
	v_sub_f32_e32 v82, v82, v0
	v_sub_f32_e32 v83, v83, v0
	v_sub_f32_e32 v84, v84, v0
	v_sub_f32_e32 v85, v85, v0
	v_sub_f32_e32 v86, v86, v0
	v_sub_f32_e32 v87, v87, v0
	v_sub_f32_e32 v88, v88, v0
	v_sub_f32_e32 v89, v89, v0
	v_sub_f32_e32 v90, v90, v0
	v_sub_f32_e32 v91, v91, v0
	v_sub_f32_e32 v92, v92, v0
	v_sub_f32_e32 v93, v93, v0
	v_sub_f32_e32 v94, v94, v0
	v_sub_f32_e32 v95, v95, v0
	v_mul_f32_e32 v16, v16, v15
	v_mul_f32_e32 v17, v17, v15
	v_mul_f32_e32 v18, v18, v15
	v_mul_f32_e32 v19, v19, v15
	v_mul_f32_e32 v20, v20, v15
	v_mul_f32_e32 v21, v21, v15
	v_mul_f32_e32 v22, v22, v15
	v_mul_f32_e32 v23, v23, v15
	v_mul_f32_e32 v24, v24, v15
	v_mul_f32_e32 v25, v25, v15
	v_mul_f32_e32 v26, v26, v15
	v_mul_f32_e32 v27, v27, v15
	v_mul_f32_e32 v28, v28, v15
	v_mul_f32_e32 v29, v29, v15
	v_mul_f32_e32 v30, v30, v15
	v_mul_f32_e32 v31, v31, v15
	v_mul_f32_e32 v32, v32, v15
	v_mul_f32_e32 v33, v33, v15
	v_mul_f32_e32 v34, v34, v15
	v_mul_f32_e32 v35, v35, v15
	v_mul_f32_e32 v36, v36, v15
	v_mul_f32_e32 v37, v37, v15
	v_mul_f32_e32 v38, v38, v15
	v_mul_f32_e32 v39, v39, v15
	v_mul_f32_e32 v40, v40, v15
	v_mul_f32_e32 v41, v41, v15
	v_mul_f32_e32 v42, v42, v15
	v_mul_f32_e32 v43, v43, v15
	v_mul_f32_e32 v44, v44, v15
	v_mul_f32_e32 v45, v45, v15
	v_mul_f32_e32 v46, v46, v15
	v_mul_f32_e32 v47, v47, v15
	v_mul_f32_e32 v48, v48, v15
	v_mul_f32_e32 v49, v49, v15
	v_mul_f32_e32 v50, v50, v15
	v_mul_f32_e32 v51, v51, v15
	v_mul_f32_e32 v52, v52, v15
	v_mul_f32_e32 v53, v53, v15
	v_mul_f32_e32 v54, v54, v15
	v_mul_f32_e32 v55, v55, v15
	v_mul_f32_e32 v56, v56, v15
	v_mul_f32_e32 v57, v57, v15
	v_mul_f32_e32 v58, v58, v15
	v_mul_f32_e32 v59, v59, v15
	v_mul_f32_e32 v60, v60, v15
	v_mul_f32_e32 v61, v61, v15
	v_mul_f32_e32 v62, v62, v15
	v_mul_f32_e32 v63, v63, v15
	v_mul_f32_e32 v64, v64, v15
	v_mul_f32_e32 v65, v65, v15
	v_mul_f32_e32 v66, v66, v15
	v_mul_f32_e32 v67, v67, v15
	v_mul_f32_e32 v68, v68, v15
	v_mul_f32_e32 v69, v69, v15
	v_mul_f32_e32 v70, v70, v15
	v_mul_f32_e32 v71, v71, v15
	v_mul_f32_e32 v72, v72, v15
	v_mul_f32_e32 v73, v73, v15
	v_mul_f32_e32 v74, v74, v15
	v_mul_f32_e32 v75, v75, v15
	v_mul_f32_e32 v76, v76, v15
	v_mul_f32_e32 v77, v77, v15
	v_mul_f32_e32 v78, v78, v15
	v_mul_f32_e32 v79, v79, v15
	v_mul_f32_e32 v159, v159, v15
	v_mov_b32_e32 v14, v0
	s_mov_b64 s[18:19], -1
	s_branch .Lfa_retA_1
.Lfa_rareB_1:
	v_mov_b32_e32 v15, v0
	s_nop 1
	v_permlane32_swap_b32_e32 v0, v15
	v_max_f32_e32 v0, v0, v15
	s_and_b64 vcc, exec, s[18:19]
	s_cbranch_vccz .Lfa_rB1_1
	v_sub_f32_e32 v192, v192, v14
	v_sub_f32_e32 v193, v193, v14
	v_sub_f32_e32 v194, v194, v14
	v_sub_f32_e32 v195, v195, v14
	v_sub_f32_e32 v196, v196, v14
	v_sub_f32_e32 v197, v197, v14
	v_sub_f32_e32 v198, v198, v14
	v_sub_f32_e32 v199, v199, v14
	v_sub_f32_e32 v200, v200, v14
	v_sub_f32_e32 v201, v201, v14
	v_sub_f32_e32 v202, v202, v14
	v_sub_f32_e32 v203, v203, v14
	v_sub_f32_e32 v204, v204, v14
	v_sub_f32_e32 v205, v205, v14
	v_sub_f32_e32 v206, v206, v14
	v_sub_f32_e32 v207, v207, v14
	v_sub_f32_e32 v208, v208, v14
	v_sub_f32_e32 v209, v209, v14
	v_sub_f32_e32 v210, v210, v14
	v_sub_f32_e32 v211, v211, v14
	v_sub_f32_e32 v212, v212, v14
	v_sub_f32_e32 v213, v213, v14
	v_sub_f32_e32 v214, v214, v14
	v_sub_f32_e32 v215, v215, v14
	v_sub_f32_e32 v216, v216, v14
	v_sub_f32_e32 v217, v217, v14
	v_sub_f32_e32 v218, v218, v14
	v_sub_f32_e32 v219, v219, v14
	v_sub_f32_e32 v220, v220, v14
	v_sub_f32_e32 v221, v221, v14
	v_sub_f32_e32 v222, v222, v14
	v_sub_f32_e32 v223, v223, v14
	v_sub_f32_e32 v0, v0, v14
	s_mov_b64 s[18:19], 0
